# grid barrier: agent-scope invalidate issued at arrival instead of after release
# speedup vs baseline: 1.0845x; 1.0079x over previous
; __device__ __forceinline__ unsigned xb_ld(unsigned* p)              { return __hip_atomic_load(p, __ATOMIC_RELAXED, __HIP_MEMORY_SCOPE_AGENT); }
; __device__ __forceinline__ unsigned xb_add(unsigned* p, unsigned v) { return __hip_atomic_fetch_add(p, v, __ATOMIC_RELAXED, __HIP_MEMORY_SCOPE_AGENT); }
; #define XB_SPIN(cond, bar) do { unsigned _sp = 0; while (cond) { __builtin_amdgcn_s_sleep(1); \
;     if ((++_sp & 255u) == 0u) { if (xb_ld(&(bar)[XB_TMO])) break; if (_sp > XB_SPIN_CAP) { atomicAdd(&(bar)[XB_TMO], 1u); break; } } } } while (0)
; __device__ __forceinline__ void xcd_barrier(const XcdBarrier& b) {
;     ...
;         unsigned nloc = b.st[0], nx = b.st[1];
;         if (nloc == 0u) { xcd_barrier_complete(bar, b.x, nloc, nx); b.st[0] = nloc; b.st[1] = nx; }
;         const unsigned old = xb_add(&bar[XB_XSUB(b.x)], 1u);
;         const unsigned gen = old / nloc;
;         if (old + 1u == (gen + 1u) * nloc) {
;             __builtin_amdgcn_fence(__ATOMIC_RELEASE, "agent");
;             asm volatile("s_waitcnt vmcnt(0)" ::: "memory");
;             const unsigned og = xb_add(&bar[XB_TOP], 1u);
;             const unsigned tg = og / nx;
;             if (og + 1u == (tg + 1u) * nx) xb_add(&bar[XB_TOPGEN], 1u);
;             else XB_SPIN(xb_ld(&bar[XB_TOPGEN]) == tg, bar);
;             __builtin_amdgcn_fence(__ATOMIC_ACQUIRE, "agent");
;             xb_add(&bar[XB_XGEN(b.x)], 1u);
;             asm volatile("s_waitcnt vmcnt(0)" ::: "memory");
;         } else {
;             XB_SPIN(xb_ld(&bar[XB_XGEN(b.x)]) == gen, bar);
.LBB0_1027:
	s_or_b64 exec, exec, s[2:3]
	v_cvt_f32_u32_e32 v5, v3
	s_waitcnt vmcnt(0)
	v_readfirstlane_b32 s2, v4
	v_sub_u32_e32 v4, 0, v3
	v_rcp_iflag_f32_e32 v5, v5
	v_add_u32_e32 v6, s2, v0
	v_mul_f32_e32 v5, 0x4f7ffffe, v5
	v_cvt_u32_f32_e32 v5, v5
	v_mul_lo_u32 v0, v4, v5
	v_mul_hi_u32 v0, v5, v0
	v_add_u32_e32 v0, v5, v0
	v_mul_hi_u32 v0, v6, v0
	v_mul_lo_u32 v4, v0, v3
	v_sub_u32_e32 v4, v6, v4
	v_add_u32_e32 v5, 1, v0
	v_cmp_ge_u32_e32 vcc, v4, v3
	s_nop 1
	v_cndmask_b32_e32 v0, v0, v5, vcc
	v_sub_u32_e32 v5, v4, v3
	v_cndmask_b32_e32 v4, v4, v5, vcc
	v_add_u32_e32 v5, 1, v0
	v_cmp_ge_u32_e32 vcc, v4, v3
	v_add_u32_e32 v4, 1, v6
	s_nop 0
	v_cndmask_b32_e32 v0, v0, v5, vcc
	v_mul_lo_u32 v5, v3, v0
	v_add_u32_e32 v3, v5, v3
	v_cmp_ne_u32_e32 vcc, v4, v3
	s_and_saveexec_b64 s[2:3], vcc
	s_xor_b64 s[2:3], exec, s[2:3]
	s_cbranch_execz .LBB0_1041
	v_readlane_b32 s4, v252, 3
	v_readlane_b32 s5, v252, 4
	s_waitcnt lgkmcnt(0)
	s_nop 3
	buffer_inv sc1
	global_load_dword v2, v1, s[4:5] sc1
	s_waitcnt vmcnt(0)
	v_cmp_eq_u32_e32 vcc, v2, v0
	s_and_saveexec_b64 s[4:5], vcc
	s_cbranch_execz .LBB0_1040
	s_mov_b32 s17, 1
	s_mov_b64 s[6:7], 0
	s_branch .LBB0_1031

; __device__ __forceinline__ unsigned xb_ld(unsigned* p)              { return __hip_atomic_load(p, __ATOMIC_RELAXED, __HIP_MEMORY_SCOPE_AGENT); }
; __device__ __forceinline__ unsigned xb_add(unsigned* p, unsigned v) { return __hip_atomic_fetch_add(p, v, __ATOMIC_RELAXED, __HIP_MEMORY_SCOPE_AGENT); }
; #define XB_SPIN(cond, bar) do { unsigned _sp = 0; while (cond) { __builtin_amdgcn_s_sleep(1); \
;     if ((++_sp & 255u) == 0u) { if (xb_ld(&(bar)[XB_TMO])) break; if (_sp > XB_SPIN_CAP) { atomicAdd(&(bar)[XB_TMO], 1u); break; } } } } while (0)
; __device__ __forceinline__ void xcd_barrier(const XcdBarrier& b) {
;     ...
;         const unsigned old = xb_add(&bar[XB_XSUB(b.x)], 1u);
;         const unsigned gen = old / nloc;
;         if (old + 1u == (gen + 1u) * nloc) {
;             __builtin_amdgcn_fence(__ATOMIC_RELEASE, "agent");
;             asm volatile("s_waitcnt vmcnt(0)" ::: "memory");
;             const unsigned og = xb_add(&bar[XB_TOP], 1u);
;             const unsigned tg = og / nx;
;             if (og + 1u == (tg + 1u) * nx) xb_add(&bar[XB_TOPGEN], 1u);
;             else XB_SPIN(xb_ld(&bar[XB_TOPGEN]) == tg, bar);
;             __builtin_amdgcn_fence(__ATOMIC_ACQUIRE, "agent");
;             xb_add(&bar[XB_XGEN(b.x)], 1u);
.LBB0_1040:
	s_or_b64 exec, exec, s[4:5]
	s_waitcnt vmcnt(0)
	s_waitcnt vmcnt(0)
.LBB0_1041:
	s_andn2_saveexec_b64 s[2:3], s[2:3]
	s_cbranch_execz .LBB0_1061
	s_mov_b64 s[2:3], exec
	buffer_wbl2 sc1
	s_waitcnt lgkmcnt(0)
	s_waitcnt vmcnt(0)
	buffer_inv sc1
	v_mbcnt_lo_u32_b32 v0, s2, 0
	v_mbcnt_hi_u32_b32 v0, s3, v0
	v_cmp_eq_u32_e32 vcc, 0, v0
	s_and_saveexec_b64 s[4:5], vcc
	s_cbranch_execz .LBB0_1044
	s_bcnt1_i32_b64 s2, s[2:3]
	v_mov_b32_e32 v3, s2
	v_readlane_b32 s2, v252, 5
	v_readlane_b32 s3, v252, 6
	s_nop 4
	global_atomic_add v3, v1, v3, s[2:3] sc0

; __device__ __forceinline__ unsigned xb_ld(unsigned* p)              { return __hip_atomic_load(p, __ATOMIC_RELAXED, __HIP_MEMORY_SCOPE_AGENT); }
; __device__ __forceinline__ unsigned xb_add(unsigned* p, unsigned v) { return __hip_atomic_fetch_add(p, v, __ATOMIC_RELAXED, __HIP_MEMORY_SCOPE_AGENT); }
; #define XB_SPIN(cond, bar) do { unsigned _sp = 0; while (cond) { __builtin_amdgcn_s_sleep(1); \
;     if ((++_sp & 255u) == 0u) { if (xb_ld(&(bar)[XB_TMO])) break; if (_sp > XB_SPIN_CAP) { atomicAdd(&(bar)[XB_TMO], 1u); break; } } } } while (0)
; __device__ __forceinline__ void xcd_barrier(const XcdBarrier& b) {
;     ...
;             const unsigned og = xb_add(&bar[XB_TOP], 1u);
;             const unsigned tg = og / nx;
;             if (og + 1u == (tg + 1u) * nx) xb_add(&bar[XB_TOPGEN], 1u);
;             else XB_SPIN(xb_ld(&bar[XB_TOPGEN]) == tg, bar);
;             __builtin_amdgcn_fence(__ATOMIC_ACQUIRE, "agent");
;             xb_add(&bar[XB_XGEN(b.x)], 1u);
;             asm volatile("s_waitcnt vmcnt(0)" ::: "memory");
.LBB0_1058:
	s_or_b64 exec, exec, s[2:3]
	s_mov_b64 s[2:3], exec
	v_mbcnt_lo_u32_b32 v0, s2, 0
	v_mbcnt_hi_u32_b32 v0, s3, v0
	v_cmp_eq_u32_e32 vcc, 0, v0
	s_waitcnt vmcnt(0)
	s_and_saveexec_b64 s[4:5], vcc
	s_cbranch_execz .LBB0_1060
	s_bcnt1_i32_b64 s2, s[2:3]
	v_mov_b32_e32 v0, s2
	v_readlane_b32 s2, v252, 3
	v_readlane_b32 s3, v252, 4
	s_nop 4
	global_atomic_add v1, v0, s[2:3]
